# layer-1 V^T epilogue, dilation-16 head group: in-place LN affine then one 16-byte store per (lane,d) (8 consecutive residue-major positions) instead of 128 two-byte stores
# speedup vs baseline: 1.0333x; 1.0333x over previous
.LBB0_756:
	s_lshl_b32 s3, s0, 8
	v_lshl_or_b32 v120, s83, 8, v199
	s_add_i32 s3, s3, s63
	v_ashrrev_i32_e32 v121, 31, v120
	v_or_b32_e32 v112, 0x80, v120
	v_lshlrev_b64 v[100:101], 2, v[120:121]
	v_ashrrev_i32_e32 v113, 31, v112
	v_or_b32_e32 v120, 0x84, v120
	v_or_b32_e32 v194, s3, v169
	v_lshlrev_b64 v[112:113], 2, v[112:113]
	v_ashrrev_i32_e32 v121, 31, v120
	v_ashrrev_i32_e32 v195, 31, v194
	v_lshl_add_u64 v[102:103], s[30:31], 0, v[100:101]
	v_lshl_add_u64 v[108:109], s[34:35], 0, v[100:101]
	v_lshl_add_u64 v[114:115], s[30:31], 0, v[112:113]
	v_lshl_add_u64 v[122:123], s[34:35], 0, v[112:113]
	v_lshl_add_u64 v[124:125], v[120:121], 2, s[30:31]
	v_lshl_add_u64 v[160:161], v[194:195], 3, s[10:11]
	global_load_dwordx4 v[96:99], v[102:103], off offset:16
	global_load_dwordx4 v[104:107], v[102:103], off
	s_nop 0
	global_load_dwordx4 v[100:103], v[108:109], off offset:16
	s_nop 0
	global_load_dwordx4 v[108:111], v[108:109], off
	s_nop 0
	global_load_dwordx4 v[112:115], v[114:115], off
	s_nop 0
	global_load_dwordx4 v[116:119], v[122:123], off
	s_nop 0
	global_load_dwordx4 v[120:123], v[122:123], off offset:16
	s_nop 0
	global_load_dwordx4 v[124:127], v[124:125], off
	s_mul_hi_i32 s0, s83, 0x55555556
	global_load_dwordx2 v[196:197], v[160:161], off
	s_lshr_b32 s1, s0, 31
	s_add_i32 s0, s0, s1
	s_mul_i32 s0, s0, 3
	s_sub_i32 s0, s83, s0
	s_lshl_b32 s1, s0, 2
	s_or_b32 s43, s1, s62
	s_lshl_b32 s2, s0, 1
	s_cmp_lt_i32 s83, 6
	s_mov_b64 s[0:1], -1
	s_cbranch_scc1 .LBB0_758
	s_cmp_lg_u32 s2, 4
	s_cbranch_scc1 .Lvt_orig_P9
	v_lshl_add_u64 v[160:161], v[194:195], 3, s[10:11]
	global_load_dwordx2 v[162:163], v[160:161], off offset:128
	global_load_dwordx2 v[208:209], v[160:161], off offset:256
	global_load_dwordx2 v[210:211], v[160:161], off offset:384
	global_load_dwordx2 v[200:201], v[160:161], off offset:1024
	global_load_dwordx2 v[252:253], v[160:161], off offset:1152
	global_load_dwordx2 v[254:255], v[160:161], off offset:1280
	global_load_dwordx2 v[248:249], v[160:161], off offset:1408
	s_waitcnt vmcnt(0)
	v_mul_f32_e32 v193, 0x3a800000, v196
	v_mul_f32_e32 v176, v193, v193
	v_fma_f32 v176, v197, s40, -v176
	v_add_f32_e32 v176, 0x3727c5ac, v176
	v_rsq_f32_e32 v195, v176
	v_fma_f32 v156, -v104, v193, v156
	v_fma_f32 v157, -v105, v193, v157
	v_fma_f32 v158, -v106, v193, v158
	v_fma_f32 v159, -v107, v193, v159
	v_fma_f32 v152, -v96, v193, v152
	v_fma_f32 v153, -v97, v193, v153
	v_fma_f32 v154, -v98, v193, v154
	v_fma_f32 v155, -v99, v193, v155
	v_fma_f32 v148, -v112, v193, v148
	v_fma_f32 v149, -v113, v193, v149
	v_fma_f32 v150, -v114, v193, v150
	v_fma_f32 v151, -v115, v193, v151
	v_fma_f32 v144, -v124, v193, v144
	v_fma_f32 v145, -v125, v193, v145
	v_fma_f32 v146, -v126, v193, v146
	v_fma_f32 v147, -v127, v193, v147
	v_fma_f32 v156, v156, v195, v108
	v_fma_f32 v157, v157, v195, v109
	v_fma_f32 v158, v158, v195, v110
	v_fma_f32 v159, v159, v195, v111
	v_fma_f32 v152, v152, v195, v100
	v_fma_f32 v153, v153, v195, v101
	v_fma_f32 v154, v154, v195, v102
	v_fma_f32 v155, v155, v195, v103
	v_fma_f32 v148, v148, v195, v116
	v_fma_f32 v149, v149, v195, v117
	v_fma_f32 v150, v150, v195, v118
	v_fma_f32 v151, v151, v195, v119
	v_fma_f32 v144, v144, v195, v120
	v_fma_f32 v145, v145, v195, v121
	v_fma_f32 v146, v146, v195, v122
	v_fma_f32 v147, v147, v195, v123
	v_mul_f32_e32 v193, 0x3a800000, v162
	v_mul_f32_e32 v176, v193, v193
	v_fma_f32 v176, v163, s40, -v176
	v_add_f32_e32 v176, 0x3727c5ac, v176
	v_rsq_f32_e32 v195, v176
	v_fma_f32 v140, -v104, v193, v140
	v_fma_f32 v141, -v105, v193, v141
	v_fma_f32 v142, -v106, v193, v142
	v_fma_f32 v143, -v107, v193, v143
	v_fma_f32 v136, -v96, v193, v136
	v_fma_f32 v137, -v97, v193, v137
	v_fma_f32 v138, -v98, v193, v138
	v_fma_f32 v139, -v99, v193, v139
	v_fma_f32 v132, -v112, v193, v132
	v_fma_f32 v133, -v113, v193, v133
	v_fma_f32 v134, -v114, v193, v134
	v_fma_f32 v135, -v115, v193, v135
	v_fma_f32 v128, -v124, v193, v128
	v_fma_f32 v129, -v125, v193, v129
	v_fma_f32 v130, -v126, v193, v130
	v_fma_f32 v131, -v127, v193, v131
	v_fma_f32 v140, v140, v195, v108
	v_fma_f32 v141, v141, v195, v109
	v_fma_f32 v142, v142, v195, v110
	v_fma_f32 v143, v143, v195, v111
	v_fma_f32 v136, v136, v195, v100
	v_fma_f32 v137, v137, v195, v101
	v_fma_f32 v138, v138, v195, v102
	v_fma_f32 v139, v139, v195, v103
	v_fma_f32 v132, v132, v195, v116
	v_fma_f32 v133, v133, v195, v117
	v_fma_f32 v134, v134, v195, v118
	v_fma_f32 v135, v135, v195, v119
	v_fma_f32 v128, v128, v195, v120
	v_fma_f32 v129, v129, v195, v121
	v_fma_f32 v130, v130, v195, v122
	v_fma_f32 v131, v131, v195, v123
	v_mul_f32_e32 v193, 0x3a800000, v208
	v_mul_f32_e32 v176, v193, v193
	v_fma_f32 v176, v209, s40, -v176
	v_add_f32_e32 v176, 0x3727c5ac, v176
	v_rsq_f32_e32 v195, v176
	v_fma_f32 v92, -v104, v193, v92
	v_fma_f32 v93, -v105, v193, v93
	v_fma_f32 v94, -v106, v193, v94
	v_fma_f32 v95, -v107, v193, v95
	v_fma_f32 v88, -v96, v193, v88
	v_fma_f32 v89, -v97, v193, v89
	v_fma_f32 v90, -v98, v193, v90
	v_fma_f32 v91, -v99, v193, v91
	v_fma_f32 v84, -v112, v193, v84
	v_fma_f32 v85, -v113, v193, v85
	v_fma_f32 v86, -v114, v193, v86
	v_fma_f32 v87, -v115, v193, v87
	v_fma_f32 v80, -v124, v193, v80
	v_fma_f32 v81, -v125, v193, v81
	v_fma_f32 v82, -v126, v193, v82
	v_fma_f32 v83, -v127, v193, v83
	v_fma_f32 v92, v92, v195, v108
	v_fma_f32 v93, v93, v195, v109
	v_fma_f32 v94, v94, v195, v110
	v_fma_f32 v95, v95, v195, v111
	v_fma_f32 v88, v88, v195, v100
	v_fma_f32 v89, v89, v195, v101
	v_fma_f32 v90, v90, v195, v102
	v_fma_f32 v91, v91, v195, v103
	v_fma_f32 v84, v84, v195, v116
	v_fma_f32 v85, v85, v195, v117
	v_fma_f32 v86, v86, v195, v118
	v_fma_f32 v87, v87, v195, v119
	v_fma_f32 v80, v80, v195, v120
	v_fma_f32 v81, v81, v195, v121
	v_fma_f32 v82, v82, v195, v122
	v_fma_f32 v83, v83, v195, v123
	v_mul_f32_e32 v193, 0x3a800000, v210
	v_mul_f32_e32 v176, v193, v193
	v_fma_f32 v176, v211, s40, -v176
	v_add_f32_e32 v176, 0x3727c5ac, v176
	v_rsq_f32_e32 v195, v176
	v_fma_f32 v76, -v104, v193, v76
	v_fma_f32 v77, -v105, v193, v77
	v_fma_f32 v78, -v106, v193, v78
	v_fma_f32 v79, -v107, v193, v79
	v_fma_f32 v72, -v96, v193, v72
	v_fma_f32 v73, -v97, v193, v73
	v_fma_f32 v74, -v98, v193, v74
	v_fma_f32 v75, -v99, v193, v75
	v_fma_f32 v68, -v112, v193, v68
	v_fma_f32 v69, -v113, v193, v69
	v_fma_f32 v70, -v114, v193, v70
	v_fma_f32 v71, -v115, v193, v71
	v_fma_f32 v64, -v124, v193, v64
	v_fma_f32 v65, -v125, v193, v65
	v_fma_f32 v66, -v126, v193, v66
	v_fma_f32 v67, -v127, v193, v67
	v_fma_f32 v76, v76, v195, v108
	v_fma_f32 v77, v77, v195, v109
	v_fma_f32 v78, v78, v195, v110
	v_fma_f32 v79, v79, v195, v111
	v_fma_f32 v72, v72, v195, v100
	v_fma_f32 v73, v73, v195, v101
	v_fma_f32 v74, v74, v195, v102
	v_fma_f32 v75, v75, v195, v103
	v_fma_f32 v68, v68, v195, v116
	v_fma_f32 v69, v69, v195, v117
	v_fma_f32 v70, v70, v195, v118
	v_fma_f32 v71, v71, v195, v119
	v_fma_f32 v64, v64, v195, v120
	v_fma_f32 v65, v65, v195, v121
	v_fma_f32 v66, v66, v195, v122
	v_fma_f32 v67, v67, v195, v123
	v_mul_f32_e32 v193, 0x3a800000, v200
	v_mul_f32_e32 v176, v193, v193
	v_fma_f32 v176, v201, s40, -v176
	v_add_f32_e32 v176, 0x3727c5ac, v176
	v_rsq_f32_e32 v195, v176
	v_fma_f32 v60, -v104, v193, v60
	v_fma_f32 v61, -v105, v193, v61
	v_fma_f32 v62, -v106, v193, v62
	v_fma_f32 v63, -v107, v193, v63
	v_fma_f32 v56, -v96, v193, v56
	v_fma_f32 v57, -v97, v193, v57
	v_fma_f32 v58, -v98, v193, v58
	v_fma_f32 v59, -v99, v193, v59
	v_fma_f32 v52, -v112, v193, v52
	v_fma_f32 v53, -v113, v193, v53
	v_fma_f32 v54, -v114, v193, v54
	v_fma_f32 v55, -v115, v193, v55
	v_fma_f32 v48, -v124, v193, v48
	v_fma_f32 v49, -v125, v193, v49
	v_fma_f32 v50, -v126, v193, v50
	v_fma_f32 v51, -v127, v193, v51
	v_fma_f32 v60, v60, v195, v108
	v_fma_f32 v61, v61, v195, v109
	v_fma_f32 v62, v62, v195, v110
	v_fma_f32 v63, v63, v195, v111
	v_fma_f32 v56, v56, v195, v100
	v_fma_f32 v57, v57, v195, v101
	v_fma_f32 v58, v58, v195, v102
	v_fma_f32 v59, v59, v195, v103
	v_fma_f32 v52, v52, v195, v116
	v_fma_f32 v53, v53, v195, v117
	v_fma_f32 v54, v54, v195, v118
	v_fma_f32 v55, v55, v195, v119
	v_fma_f32 v48, v48, v195, v120
	v_fma_f32 v49, v49, v195, v121
	v_fma_f32 v50, v50, v195, v122
	v_fma_f32 v51, v51, v195, v123
	v_mul_f32_e32 v193, 0x3a800000, v252
	v_mul_f32_e32 v176, v193, v193
	v_fma_f32 v176, v253, s40, -v176
	v_add_f32_e32 v176, 0x3727c5ac, v176
	v_rsq_f32_e32 v195, v176
	v_fma_f32 v44, -v104, v193, v44
	v_fma_f32 v45, -v105, v193, v45
	v_fma_f32 v46, -v106, v193, v46
	v_fma_f32 v47, -v107, v193, v47
	v_fma_f32 v40, -v96, v193, v40
	v_fma_f32 v41, -v97, v193, v41
	v_fma_f32 v42, -v98, v193, v42
	v_fma_f32 v43, -v99, v193, v43
	v_fma_f32 v36, -v112, v193, v36
	v_fma_f32 v37, -v113, v193, v37
	v_fma_f32 v38, -v114, v193, v38
	v_fma_f32 v39, -v115, v193, v39
	v_fma_f32 v32, -v124, v193, v32
	v_fma_f32 v33, -v125, v193, v33
	v_fma_f32 v34, -v126, v193, v34
	v_fma_f32 v35, -v127, v193, v35
	v_fma_f32 v44, v44, v195, v108
	v_fma_f32 v45, v45, v195, v109
	v_fma_f32 v46, v46, v195, v110
	v_fma_f32 v47, v47, v195, v111
	v_fma_f32 v40, v40, v195, v100
	v_fma_f32 v41, v41, v195, v101
	v_fma_f32 v42, v42, v195, v102
	v_fma_f32 v43, v43, v195, v103
	v_fma_f32 v36, v36, v195, v116
	v_fma_f32 v37, v37, v195, v117
	v_fma_f32 v38, v38, v195, v118
	v_fma_f32 v39, v39, v195, v119
	v_fma_f32 v32, v32, v195, v120
	v_fma_f32 v33, v33, v195, v121
	v_fma_f32 v34, v34, v195, v122
	v_fma_f32 v35, v35, v195, v123
	v_mul_f32_e32 v193, 0x3a800000, v254
	v_mul_f32_e32 v176, v193, v193
	v_fma_f32 v176, v255, s40, -v176
	v_add_f32_e32 v176, 0x3727c5ac, v176
	v_rsq_f32_e32 v195, v176
	v_fma_f32 v28, -v104, v193, v28
	v_fma_f32 v29, -v105, v193, v29
	v_fma_f32 v30, -v106, v193, v30
	v_fma_f32 v31, -v107, v193, v31
	v_fma_f32 v24, -v96, v193, v24
	v_fma_f32 v25, -v97, v193, v25
	v_fma_f32 v26, -v98, v193, v26
	v_fma_f32 v27, -v99, v193, v27
	v_fma_f32 v20, -v112, v193, v20
	v_fma_f32 v21, -v113, v193, v21
	v_fma_f32 v22, -v114, v193, v22
	v_fma_f32 v23, -v115, v193, v23
	v_fma_f32 v16, -v124, v193, v16
	v_fma_f32 v17, -v125, v193, v17
	v_fma_f32 v18, -v126, v193, v18
	v_fma_f32 v19, -v127, v193, v19
	v_fma_f32 v28, v28, v195, v108
	v_fma_f32 v29, v29, v195, v109
	v_fma_f32 v30, v30, v195, v110
	v_fma_f32 v31, v31, v195, v111
	v_fma_f32 v24, v24, v195, v100
	v_fma_f32 v25, v25, v195, v101
	v_fma_f32 v26, v26, v195, v102
	v_fma_f32 v27, v27, v195, v103
	v_fma_f32 v20, v20, v195, v116
	v_fma_f32 v21, v21, v195, v117
	v_fma_f32 v22, v22, v195, v118
	v_fma_f32 v23, v23, v195, v119
	v_fma_f32 v16, v16, v195, v120
	v_fma_f32 v17, v17, v195, v121
	v_fma_f32 v18, v18, v195, v122
	v_fma_f32 v19, v19, v195, v123
	v_mul_f32_e32 v193, 0x3a800000, v248
	v_mul_f32_e32 v176, v193, v193
	v_fma_f32 v176, v249, s40, -v176
	v_add_f32_e32 v176, 0x3727c5ac, v176
	v_rsq_f32_e32 v195, v176
	v_fma_f32 v12, -v104, v193, v12
	v_fma_f32 v13, -v105, v193, v13
	v_fma_f32 v14, -v106, v193, v14
	v_fma_f32 v15, -v107, v193, v15
	v_fma_f32 v8, -v96, v193, v8
	v_fma_f32 v9, -v97, v193, v9
	v_fma_f32 v10, -v98, v193, v10
	v_fma_f32 v11, -v99, v193, v11
	v_fma_f32 v4, -v112, v193, v4
	v_fma_f32 v5, -v113, v193, v5
	v_fma_f32 v6, -v114, v193, v6
	v_fma_f32 v7, -v115, v193, v7
	v_fma_f32 v0, -v124, v193, v0
	v_fma_f32 v1, -v125, v193, v1
	v_fma_f32 v2, -v126, v193, v2
	v_fma_f32 v3, -v127, v193, v3
	v_fma_f32 v12, v12, v195, v108
	v_fma_f32 v13, v13, v195, v109
	v_fma_f32 v14, v14, v195, v110
	v_fma_f32 v15, v15, v195, v111
	v_fma_f32 v8, v8, v195, v100
	v_fma_f32 v9, v9, v195, v101
	v_fma_f32 v10, v10, v195, v102
	v_fma_f32 v11, v11, v195, v103
	v_fma_f32 v4, v4, v195, v116
	v_fma_f32 v5, v5, v195, v117
	v_fma_f32 v6, v6, v195, v118
	v_fma_f32 v7, v7, v195, v119
	v_fma_f32 v0, v0, v195, v120
	v_fma_f32 v1, v1, v195, v121
	v_fma_f32 v2, v2, v195, v122
	v_fma_f32 v3, v3, v195, v123
	s_sub_i32 s45, 13, s2
	v_and_b32_e32 v162, 0x1fcf, v194
	v_lshlrev_b32_e32 v160, s45, v194
	v_and_b32_e32 v163, 0x1ffe, v160
	v_lshrrev_b32_e32 v176, s2, v162
	v_or_b32_e32 v193, v163, v176
	v_bitop3_b32 v163, v163, s72, v176 bitop3:0xc8
	v_lshlrev_b32_e32 v176, 1, v193
	v_lshrrev_b32_e32 v193, 1, v193
	v_and_b32_e32 v176, 8, v176
	v_and_b32_e32 v193, 4, v193
	v_or3_b32 v163, v176, v163, v193
	s_ashr_i32 s0, s3, 13
	s_mul_i32 s0, s0, 12
	s_add_i32 s0, s0, s43
	s_ashr_i32 s1, s0, 31
	s_lshl_b64 s[0:1], s[0:1], 20
	v_lshl_add_u64 v[160:161], v[182:183], 0, s[0:1]
	v_lshlrev_b32_e32 v176, 1, v163
	v_lshl_add_u64 v[200:201], v[160:161], 0, v[176:177]
	v_cvt_pk_bf16_f32 v96, v156, v140
	v_cvt_pk_bf16_f32 v97, v92, v76
	v_cvt_pk_bf16_f32 v98, v60, v44
	v_cvt_pk_bf16_f32 v99, v28, v12
	global_store_dwordx4 v[200:201], v[96:99], off
	v_cvt_pk_bf16_f32 v100, v157, v141
	v_cvt_pk_bf16_f32 v101, v93, v77
	v_cvt_pk_bf16_f32 v102, v61, v45
	v_cvt_pk_bf16_f32 v103, v29, v13
	v_add_co_u32_e32 v162, vcc, s61, v200
	s_nop 1
	v_addc_co_u32_e32 v163, vcc, 0, v201, vcc
	global_store_dwordx4 v[162:163], v[100:103], off
	v_cvt_pk_bf16_f32 v104, v158, v142
	v_cvt_pk_bf16_f32 v105, v94, v78
	v_cvt_pk_bf16_f32 v106, v62, v46
	v_cvt_pk_bf16_f32 v107, v30, v14
	v_add_co_u32_e32 v160, vcc, s67, v200
	s_nop 1
	v_addc_co_u32_e32 v161, vcc, 0, v201, vcc
	global_store_dwordx4 v[160:161], v[104:107], off
	v_cvt_pk_bf16_f32 v108, v159, v143
	v_cvt_pk_bf16_f32 v109, v95, v79
	v_cvt_pk_bf16_f32 v110, v63, v47
	v_cvt_pk_bf16_f32 v111, v31, v15
	v_add_co_u32_e32 v162, vcc, s71, v200
	s_nop 1
	v_addc_co_u32_e32 v163, vcc, 0, v201, vcc
	global_store_dwordx4 v[162:163], v[108:111], off
	v_cvt_pk_bf16_f32 v96, v152, v136
	v_cvt_pk_bf16_f32 v97, v88, v72
	v_cvt_pk_bf16_f32 v98, v56, v40
	v_cvt_pk_bf16_f32 v99, v24, v8
	v_add_co_u32_e32 v160, vcc, s59, v200
	s_nop 1
	v_addc_co_u32_e32 v161, vcc, 0, v201, vcc
	global_store_dwordx4 v[160:161], v[96:99], off
	v_cvt_pk_bf16_f32 v100, v153, v137
	v_cvt_pk_bf16_f32 v101, v89, v73
	v_cvt_pk_bf16_f32 v102, v57, v41
	v_cvt_pk_bf16_f32 v103, v25, v9
	v_add_co_u32_e32 v162, vcc, s60, v200
	s_nop 1
	v_addc_co_u32_e32 v163, vcc, 0, v201, vcc
	global_store_dwordx4 v[162:163], v[100:103], off
	v_cvt_pk_bf16_f32 v104, v154, v138
	v_cvt_pk_bf16_f32 v105, v90, v74
	v_cvt_pk_bf16_f32 v106, v58, v42
	v_cvt_pk_bf16_f32 v107, v26, v10
	v_add_co_u32_e32 v160, vcc, s66, v200
	s_nop 1
	v_addc_co_u32_e32 v161, vcc, 0, v201, vcc
	global_store_dwordx4 v[160:161], v[104:107], off
	v_cvt_pk_bf16_f32 v108, v155, v139
	v_cvt_pk_bf16_f32 v109, v91, v75
	v_cvt_pk_bf16_f32 v110, v59, v43
	v_cvt_pk_bf16_f32 v111, v27, v11
	v_add_co_u32_e32 v162, vcc, s68, v200
	s_nop 1
	v_addc_co_u32_e32 v163, vcc, 0, v201, vcc
	global_store_dwordx4 v[162:163], v[108:111], off
	v_cvt_pk_bf16_f32 v96, v148, v132
	v_cvt_pk_bf16_f32 v97, v84, v68
	v_cvt_pk_bf16_f32 v98, v52, v36
	v_cvt_pk_bf16_f32 v99, v20, v4
	v_add_co_u32_e32 v160, vcc, s74, v200
	s_nop 1
	v_addc_co_u32_e32 v161, vcc, 0, v201, vcc
	global_store_dwordx4 v[160:161], v[96:99], off
	v_cvt_pk_bf16_f32 v100, v149, v133
	v_cvt_pk_bf16_f32 v101, v85, v69
	v_cvt_pk_bf16_f32 v102, v53, v37
	v_cvt_pk_bf16_f32 v103, v21, v5
	v_add_co_u32_e32 v162, vcc, s75, v200
	s_nop 1
	v_addc_co_u32_e32 v163, vcc, 0, v201, vcc
	global_store_dwordx4 v[162:163], v[100:103], off
	v_cvt_pk_bf16_f32 v104, v150, v134
	v_cvt_pk_bf16_f32 v105, v86, v70
	v_cvt_pk_bf16_f32 v106, v54, v38
	v_cvt_pk_bf16_f32 v107, v22, v6
	v_add_co_u32_e32 v160, vcc, s76, v200
	s_nop 1
	v_addc_co_u32_e32 v161, vcc, 0, v201, vcc
	global_store_dwordx4 v[160:161], v[104:107], off
	v_cvt_pk_bf16_f32 v108, v151, v135
	v_cvt_pk_bf16_f32 v109, v87, v71
	v_cvt_pk_bf16_f32 v110, v55, v39
	v_cvt_pk_bf16_f32 v111, v23, v7
	v_add_co_u32_e32 v162, vcc, s77, v200
	s_nop 1
	v_addc_co_u32_e32 v163, vcc, 0, v201, vcc
	global_store_dwordx4 v[162:163], v[108:111], off
	v_cvt_pk_bf16_f32 v96, v144, v128
	v_cvt_pk_bf16_f32 v97, v80, v64
	v_cvt_pk_bf16_f32 v98, v48, v32
	v_cvt_pk_bf16_f32 v99, v16, v0
	v_add_co_u32_e32 v160, vcc, s78, v200
	s_nop 1
	v_addc_co_u32_e32 v161, vcc, 0, v201, vcc
	global_store_dwordx4 v[160:161], v[96:99], off
	v_cvt_pk_bf16_f32 v100, v145, v129
	v_cvt_pk_bf16_f32 v101, v81, v65
	v_cvt_pk_bf16_f32 v102, v49, v33
	v_cvt_pk_bf16_f32 v103, v17, v1
	v_add_co_u32_e32 v162, vcc, s79, v200
	s_nop 1
	v_addc_co_u32_e32 v163, vcc, 0, v201, vcc
	global_store_dwordx4 v[162:163], v[100:103], off
	v_cvt_pk_bf16_f32 v104, v146, v130
	v_cvt_pk_bf16_f32 v105, v82, v66
	v_cvt_pk_bf16_f32 v106, v50, v34
	v_cvt_pk_bf16_f32 v107, v18, v2
	v_add_co_u32_e32 v160, vcc, s80, v200
	s_nop 1
	v_addc_co_u32_e32 v161, vcc, 0, v201, vcc
	global_store_dwordx4 v[160:161], v[104:107], off
	v_cvt_pk_bf16_f32 v108, v147, v131
	v_cvt_pk_bf16_f32 v109, v83, v67
	v_cvt_pk_bf16_f32 v110, v51, v35
	v_cvt_pk_bf16_f32 v111, v19, v3
	v_add_co_u32_e32 v162, vcc, s81, v200
	s_nop 1
	v_addc_co_u32_e32 v163, vcc, 0, v201, vcc
	global_store_dwordx4 v[162:163], v[108:111], off
	s_mov_b64 s[0:1], 0
	s_branch .LBB0_758
.Lvt_orig_P9:
	s_sub_i32 s45, 13, s2
	v_and_b32_e32 v162, 0x1fcf, v194
	v_lshlrev_b32_e32 v160, s45, v194
	v_and_b32_e32 v163, 0x1ffe, v160
	v_lshrrev_b32_e32 v176, s2, v162
	v_or_b32_e32 v193, v163, v176
	v_bitop3_b32 v163, v163, s72, v176 bitop3:0xc8
	v_lshlrev_b32_e32 v176, 1, v193
	v_lshrrev_b32_e32 v193, 1, v193
	v_and_b32_e32 v176, 8, v176
	v_and_b32_e32 v193, 4, v193
	v_or3_b32 v163, v176, v163, v193
	s_waitcnt vmcnt(0)
	v_mul_f32_e32 v193, 0x3a800000, v196
	v_mul_f32_e32 v176, v193, v193
	v_fma_f32 v176, v197, s40, -v176
	v_or_b32_e32 v208, 16, v194
	v_add_f32_e32 v176, 0x3727c5ac, v176
	v_ashrrev_i32_e32 v209, 31, v208
	v_mul_f32_e32 v195, 0x4f800000, v176
	v_cmp_gt_f32_e32 vcc, s73, v176
	v_lshl_add_u64 v[208:209], v[208:209], 3, s[10:11]
	s_ashr_i32 s0, s3, 13
	v_cndmask_b32_e32 v195, v176, v195, vcc
	global_load_dwordx2 v[208:209], v[208:209], off
	s_mul_i32 s0, s0, 12
	v_sqrt_f32_e32 v198, v195
	s_add_i32 s0, s0, s43
	s_ashr_i32 s1, s0, 31
	s_lshl_b64 s[0:1], s[0:1], 20
	v_lshl_add_u64 v[160:161], v[182:183], 0, s[0:1]
	v_lshlrev_b32_e32 v176, 1, v163
	v_add_u32_e32 v163, -1, v198
	v_lshl_add_u64 v[200:201], v[160:161], 0, v[176:177]
	v_fma_f32 v176, -v163, v198, v195
	v_cmp_ge_f32_e64 s[0:1], 0, v176
	v_add_u32_e32 v176, 1, v198
	s_nop 0
	v_cndmask_b32_e64 v163, v198, v163, s[0:1]
	v_fma_f32 v198, -v176, v198, v195
	v_cmp_lt_f32_e64 s[0:1], 0, v198
	s_nop 1
	v_cndmask_b32_e64 v163, v163, v176, s[0:1]
	v_mul_f32_e32 v176, 0x37800000, v163
	v_cndmask_b32_e32 v163, v163, v176, vcc
	v_cmp_class_f32_e32 vcc, v195, v205
	s_nop 1
	v_cndmask_b32_e32 v163, v163, v195, vcc
	v_div_scale_f32 v176, s[0:1], v163, v163, 1.0
	v_rcp_f32_e32 v195, v176
	s_nop 0
	v_fma_f32 v198, -v176, v195, 1.0
	v_fmac_f32_e32 v195, v198, v195
	v_div_scale_f32 v198, vcc, 1.0, v163, 1.0
	v_mul_f32_e32 v207, v198, v195
	v_fma_f32 v210, -v176, v207, v198
	v_fmac_f32_e32 v207, v210, v195
	v_fma_f32 v176, -v176, v207, v198
	v_div_fmas_f32 v176, v176, v195, v207
	v_div_fixup_f32 v163, v176, v163, 1.0
	v_fma_f32 v176, -v104, v193, v156
	v_fma_f32 v176, v176, v163, v108
	v_cvt_pk_bf16_f32 v176, v176, s0
	global_store_short v[200:201], v176, off
	v_fma_f32 v176, -v105, v193, v157
	v_fma_f32 v176, v176, v163, v109
	v_add_co_u32_e32 v210, vcc, s61, v200
	v_cvt_pk_bf16_f32 v176, v176, s0
	s_nop 0
	v_addc_co_u32_e32 v211, vcc, 0, v201, vcc
	global_store_short v[210:211], v176, off
	v_fma_f32 v176, -v106, v193, v158
	v_fma_f32 v176, v176, v163, v110
	v_add_co_u32_e32 v210, vcc, s67, v200
	v_cvt_pk_bf16_f32 v176, v176, s0
	s_nop 0
	v_addc_co_u32_e32 v211, vcc, 0, v201, vcc
	global_store_short v[210:211], v176, off
	v_fma_f32 v176, -v107, v193, v159
	v_fma_f32 v176, v176, v163, v111
	v_add_co_u32_e32 v210, vcc, s71, v200
	v_cvt_pk_bf16_f32 v176, v176, s0
	s_nop 0
	v_addc_co_u32_e32 v211, vcc, 0, v201, vcc
	global_store_short v[210:211], v176, off
	v_fma_f32 v176, -v96, v193, v152
	v_fma_f32 v176, v176, v163, v100
	v_add_co_u32_e32 v210, vcc, s59, v200
	v_cvt_pk_bf16_f32 v176, v176, s0
	s_nop 0
	v_addc_co_u32_e32 v211, vcc, 0, v201, vcc
	global_store_short v[210:211], v176, off
	v_fma_f32 v176, -v97, v193, v153
	v_fma_f32 v176, v176, v163, v101
	v_add_co_u32_e32 v210, vcc, s60, v200
	v_cvt_pk_bf16_f32 v176, v176, s0
	s_nop 0
	v_addc_co_u32_e32 v211, vcc, 0, v201, vcc
	global_store_short v[210:211], v176, off
	v_fma_f32 v176, -v98, v193, v154
	v_fma_f32 v176, v176, v163, v102
	v_add_co_u32_e32 v210, vcc, s66, v200
	v_cvt_pk_bf16_f32 v176, v176, s0
	s_nop 0
	v_addc_co_u32_e32 v211, vcc, 0, v201, vcc
	global_store_short v[210:211], v176, off
	v_fma_f32 v176, -v99, v193, v155
	v_fma_f32 v176, v176, v163, v103
	v_add_co_u32_e32 v210, vcc, s68, v200
	v_cvt_pk_bf16_f32 v176, v176, s0
	s_nop 0
	v_addc_co_u32_e32 v211, vcc, 0, v201, vcc
	global_store_short v[210:211], v176, off
	v_fma_f32 v176, -v112, v193, v148
	v_fma_f32 v176, v176, v163, v116
	v_add_co_u32_e32 v210, vcc, s74, v200
	v_cvt_pk_bf16_f32 v176, v176, s0
	s_nop 0
	v_addc_co_u32_e32 v211, vcc, 0, v201, vcc
	global_store_short v[210:211], v176, off
	v_fma_f32 v176, -v113, v193, v149
	v_fma_f32 v176, v176, v163, v117
	v_add_co_u32_e32 v210, vcc, s75, v200
	v_cvt_pk_bf16_f32 v176, v176, s0
	s_nop 0
	v_addc_co_u32_e32 v211, vcc, 0, v201, vcc
	global_store_short v[210:211], v176, off
	v_fma_f32 v176, -v114, v193, v150
	v_fma_f32 v176, v176, v163, v118
	v_add_co_u32_e32 v210, vcc, s76, v200
	v_cvt_pk_bf16_f32 v176, v176, s0
	s_nop 0
	v_addc_co_u32_e32 v211, vcc, 0, v201, vcc
	global_store_short v[210:211], v176, off
	v_fma_f32 v176, -v115, v193, v151
	v_fma_f32 v176, v176, v163, v119
	v_add_co_u32_e32 v210, vcc, s77, v200
	v_cvt_pk_bf16_f32 v176, v176, s0
	s_nop 0
	v_addc_co_u32_e32 v211, vcc, 0, v201, vcc
	global_store_short v[210:211], v176, off
	v_fma_f32 v176, -v124, v193, v144
	v_fma_f32 v176, v176, v163, v120
	v_add_co_u32_e32 v210, vcc, s78, v200
	v_cvt_pk_bf16_f32 v176, v176, s0
	s_nop 0
	v_addc_co_u32_e32 v211, vcc, 0, v201, vcc
	global_store_short v[210:211], v176, off
	v_fma_f32 v176, -v125, v193, v145
	v_fma_f32 v176, v176, v163, v121
	v_add_co_u32_e32 v210, vcc, s79, v200
	v_cvt_pk_bf16_f32 v176, v176, s0
	s_nop 0
	v_addc_co_u32_e32 v211, vcc, 0, v201, vcc
	global_store_short v[210:211], v176, off
	v_fma_f32 v176, -v126, v193, v146
	v_fma_f32 v176, v176, v163, v122
	v_add_co_u32_e32 v210, vcc, s80, v200
	v_cvt_pk_bf16_f32 v176, v176, s0
	s_nop 0
	v_addc_co_u32_e32 v211, vcc, 0, v201, vcc
	global_store_short v[210:211], v176, off
	v_fma_f32 v176, -v127, v193, v147
	v_fma_f32 v163, v176, v163, v123
	v_add_co_u32_e32 v200, vcc, s81, v200
	v_cvt_pk_bf16_f32 v163, v163, s0
	s_nop 0
	v_addc_co_u32_e32 v201, vcc, 0, v201, vcc
	global_store_short v[200:201], v163, off
	v_or_b32_e32 v163, 16, v162
	v_lshlrev_b32_e32 v176, s45, v163
	v_and_b32_e32 v176, 0x1ffe, v176
	v_lshrrev_b32_e32 v163, s2, v163
	v_or_b32_e32 v193, v176, v163
	v_bitop3_b32 v163, v176, s72, v163 bitop3:0xc8
	v_lshlrev_b32_e32 v176, 1, v193
	v_lshrrev_b32_e32 v193, 1, v193
	v_and_b32_e32 v176, 8, v176
	v_and_b32_e32 v193, 4, v193
	v_or3_b32 v163, v176, v163, v193
	s_waitcnt vmcnt(16)
	v_mul_f32_e32 v193, 0x3a800000, v208
	v_mul_f32_e32 v176, v193, v193
	v_fma_f32 v176, v209, s40, -v176
	v_or_b32_e32 v208, 32, v194
	v_add_f32_e32 v176, 0x3727c5ac, v176
	v_ashrrev_i32_e32 v209, 31, v208
	v_mul_f32_e32 v195, 0x4f800000, v176
	v_cmp_gt_f32_e32 vcc, s73, v176
	v_lshl_add_u64 v[208:209], v[208:209], 3, s[10:11]
	global_load_dwordx2 v[208:209], v[208:209], off
	v_cndmask_b32_e32 v195, v176, v195, vcc
	v_sqrt_f32_e32 v198, v195
	v_lshlrev_b32_e32 v176, 1, v163
	v_lshl_add_u64 v[200:201], v[160:161], 0, v[176:177]
	v_add_u32_e32 v163, -1, v198
	v_fma_f32 v176, -v163, v198, v195
	v_cmp_ge_f32_e64 s[0:1], 0, v176
	v_add_u32_e32 v176, 1, v198
	s_nop 0
	v_cndmask_b32_e64 v163, v198, v163, s[0:1]
	v_fma_f32 v198, -v176, v198, v195
	v_cmp_lt_f32_e64 s[0:1], 0, v198
	s_nop 1
	v_cndmask_b32_e64 v163, v163, v176, s[0:1]
	v_mul_f32_e32 v176, 0x37800000, v163
	v_cndmask_b32_e32 v163, v163, v176, vcc
	v_cmp_class_f32_e32 vcc, v195, v205
	s_nop 1
	v_cndmask_b32_e32 v163, v163, v195, vcc
	v_div_scale_f32 v176, s[0:1], v163, v163, 1.0
	v_rcp_f32_e32 v195, v176
	s_nop 0
	v_fma_f32 v198, -v176, v195, 1.0
	v_fmac_f32_e32 v195, v198, v195
	v_div_scale_f32 v198, vcc, 1.0, v163, 1.0
	v_mul_f32_e32 v207, v198, v195
	v_fma_f32 v210, -v176, v207, v198
	v_fmac_f32_e32 v207, v210, v195
	v_fma_f32 v176, -v176, v207, v198
	v_div_fmas_f32 v176, v176, v195, v207
	v_div_fixup_f32 v163, v176, v163, 1.0
	v_fma_f32 v176, -v104, v193, v140
	v_fma_f32 v176, v176, v163, v108
	v_cvt_pk_bf16_f32 v176, v176, s0
	global_store_short v[200:201], v176, off
	v_fma_f32 v176, -v105, v193, v141
	v_fma_f32 v176, v176, v163, v109
	v_add_co_u32_e32 v210, vcc, s61, v200
	v_cvt_pk_bf16_f32 v176, v176, s0
	s_nop 0
	v_addc_co_u32_e32 v211, vcc, 0, v201, vcc
	global_store_short v[210:211], v176, off
	v_fma_f32 v176, -v106, v193, v142
	v_fma_f32 v176, v176, v163, v110
	v_add_co_u32_e32 v210, vcc, s67, v200
	v_cvt_pk_bf16_f32 v176, v176, s0
	s_nop 0
	v_addc_co_u32_e32 v211, vcc, 0, v201, vcc
	global_store_short v[210:211], v176, off
	v_fma_f32 v176, -v107, v193, v143
	v_fma_f32 v176, v176, v163, v111
	v_add_co_u32_e32 v210, vcc, s71, v200
	v_cvt_pk_bf16_f32 v176, v176, s0
	s_nop 0
	v_addc_co_u32_e32 v211, vcc, 0, v201, vcc
	global_store_short v[210:211], v176, off
	v_fma_f32 v176, -v96, v193, v136
	v_fma_f32 v176, v176, v163, v100
	v_add_co_u32_e32 v210, vcc, s59, v200
	v_cvt_pk_bf16_f32 v176, v176, s0
	s_nop 0
	v_addc_co_u32_e32 v211, vcc, 0, v201, vcc
	global_store_short v[210:211], v176, off
	v_fma_f32 v176, -v97, v193, v137
	v_fma_f32 v176, v176, v163, v101
	v_add_co_u32_e32 v210, vcc, s60, v200
	v_cvt_pk_bf16_f32 v176, v176, s0
	s_nop 0
	v_addc_co_u32_e32 v211, vcc, 0, v201, vcc
	global_store_short v[210:211], v176, off
	v_fma_f32 v176, -v98, v193, v138
	v_fma_f32 v176, v176, v163, v102
	v_add_co_u32_e32 v210, vcc, s66, v200
	v_cvt_pk_bf16_f32 v176, v176, s0
	s_nop 0
	v_addc_co_u32_e32 v211, vcc, 0, v201, vcc
	global_store_short v[210:211], v176, off
	v_fma_f32 v176, -v99, v193, v139
	v_fma_f32 v176, v176, v163, v103
	v_add_co_u32_e32 v210, vcc, s68, v200
	v_cvt_pk_bf16_f32 v176, v176, s0
	s_nop 0
	v_addc_co_u32_e32 v211, vcc, 0, v201, vcc
	global_store_short v[210:211], v176, off
	v_fma_f32 v176, -v112, v193, v132
	v_fma_f32 v176, v176, v163, v116
	v_add_co_u32_e32 v210, vcc, s74, v200
	v_cvt_pk_bf16_f32 v176, v176, s0
	s_nop 0
	v_addc_co_u32_e32 v211, vcc, 0, v201, vcc
	global_store_short v[210:211], v176, off
	v_fma_f32 v176, -v113, v193, v133
	v_fma_f32 v176, v176, v163, v117
	v_add_co_u32_e32 v210, vcc, s75, v200
	v_cvt_pk_bf16_f32 v176, v176, s0
	s_nop 0
	v_addc_co_u32_e32 v211, vcc, 0, v201, vcc
	global_store_short v[210:211], v176, off
	v_fma_f32 v176, -v114, v193, v134
	v_fma_f32 v176, v176, v163, v118
	v_add_co_u32_e32 v210, vcc, s76, v200
	v_cvt_pk_bf16_f32 v176, v176, s0
	s_nop 0
	v_addc_co_u32_e32 v211, vcc, 0, v201, vcc
	global_store_short v[210:211], v176, off
	v_fma_f32 v176, -v115, v193, v135
	v_fma_f32 v176, v176, v163, v119
	v_add_co_u32_e32 v210, vcc, s77, v200
	v_cvt_pk_bf16_f32 v176, v176, s0
	s_nop 0
	v_addc_co_u32_e32 v211, vcc, 0, v201, vcc
	global_store_short v[210:211], v176, off
	v_fma_f32 v176, -v124, v193, v128
	v_fma_f32 v176, v176, v163, v120
	v_add_co_u32_e32 v210, vcc, s78, v200
	v_cvt_pk_bf16_f32 v176, v176, s0
	s_nop 0
	v_addc_co_u32_e32 v211, vcc, 0, v201, vcc
	global_store_short v[210:211], v176, off
	v_fma_f32 v176, -v125, v193, v129
	v_fma_f32 v176, v176, v163, v121
	v_add_co_u32_e32 v210, vcc, s79, v200
	v_cvt_pk_bf16_f32 v176, v176, s0
	s_nop 0
	v_addc_co_u32_e32 v211, vcc, 0, v201, vcc
	global_store_short v[210:211], v176, off
	v_fma_f32 v176, -v126, v193, v130
	v_fma_f32 v176, v176, v163, v122
	v_add_co_u32_e32 v210, vcc, s80, v200
	v_cvt_pk_bf16_f32 v176, v176, s0
	s_nop 0
	v_addc_co_u32_e32 v211, vcc, 0, v201, vcc
	global_store_short v[210:211], v176, off
	v_fma_f32 v176, -v127, v193, v131
	v_fma_f32 v163, v176, v163, v123
	v_add_co_u32_e32 v200, vcc, s81, v200
	v_cvt_pk_bf16_f32 v163, v163, s0
	s_nop 0
	v_addc_co_u32_e32 v201, vcc, 0, v201, vcc
	global_store_short v[200:201], v163, off
	v_or_b32_e32 v163, 32, v162
	v_lshlrev_b32_e32 v176, s45, v163
	v_and_b32_e32 v176, 0x1ffe, v176
	v_lshrrev_b32_e32 v163, s2, v163
	v_or_b32_e32 v193, v176, v163
	v_bitop3_b32 v163, v176, s72, v163 bitop3:0xc8
	v_lshlrev_b32_e32 v176, 1, v193
	v_lshrrev_b32_e32 v193, 1, v193
	v_and_b32_e32 v176, 8, v176
	v_and_b32_e32 v193, 4, v193
	v_or3_b32 v163, v176, v163, v193
	s_waitcnt vmcnt(16)
	v_mul_f32_e32 v193, 0x3a800000, v208
	v_mul_f32_e32 v176, v193, v193
	v_or_b32_e32 v208, 48, v194
	v_fma_f32 v176, v209, s40, -v176
	v_ashrrev_i32_e32 v209, 31, v208
	v_lshl_add_u64 v[208:209], v[208:209], 3, s[10:11]
	v_add_f32_e32 v176, 0x3727c5ac, v176
	global_load_dwordx2 v[208:209], v[208:209], off
	v_mul_f32_e32 v195, 0x4f800000, v176
	v_cmp_gt_f32_e32 vcc, s73, v176
	v_or_b32_e32 v162, 48, v162
	s_nop 0
	v_cndmask_b32_e32 v195, v176, v195, vcc
	v_sqrt_f32_e32 v198, v195
	v_lshlrev_b32_e32 v176, 1, v163
	v_lshl_add_u64 v[200:201], v[160:161], 0, v[176:177]
	v_add_u32_e32 v163, -1, v198
	v_fma_f32 v176, -v163, v198, v195
	v_cmp_ge_f32_e64 s[0:1], 0, v176
	v_add_u32_e32 v176, 1, v198
	s_nop 0
	v_cndmask_b32_e64 v163, v198, v163, s[0:1]
	v_fma_f32 v198, -v176, v198, v195
	v_cmp_lt_f32_e64 s[0:1], 0, v198
	s_nop 1
	v_cndmask_b32_e64 v163, v163, v176, s[0:1]
	v_mul_f32_e32 v176, 0x37800000, v163
	v_cndmask_b32_e32 v163, v163, v176, vcc
	v_cmp_class_f32_e32 vcc, v195, v205
	s_nop 1
	v_cndmask_b32_e32 v163, v163, v195, vcc
	v_div_scale_f32 v176, s[0:1], v163, v163, 1.0
	v_rcp_f32_e32 v195, v176
	s_nop 0
	v_fma_f32 v198, -v176, v195, 1.0
	v_fmac_f32_e32 v195, v198, v195
	v_div_scale_f32 v198, vcc, 1.0, v163, 1.0
	v_mul_f32_e32 v207, v198, v195
	v_fma_f32 v210, -v176, v207, v198
	v_fmac_f32_e32 v207, v210, v195
	v_fma_f32 v176, -v176, v207, v198
	v_div_fmas_f32 v176, v176, v195, v207
	v_div_fixup_f32 v163, v176, v163, 1.0
	v_fma_f32 v176, -v104, v193, v92
	v_fma_f32 v176, v176, v163, v108
	v_cvt_pk_bf16_f32 v176, v176, s0
	global_store_short v[200:201], v176, off
	v_fma_f32 v176, -v105, v193, v93
	v_fma_f32 v176, v176, v163, v109
	v_add_co_u32_e32 v210, vcc, s61, v200
	v_cvt_pk_bf16_f32 v176, v176, s0
	s_nop 0
	v_addc_co_u32_e32 v211, vcc, 0, v201, vcc
	global_store_short v[210:211], v176, off
	v_fma_f32 v176, -v106, v193, v94
	v_fma_f32 v176, v176, v163, v110
	v_add_co_u32_e32 v210, vcc, s67, v200
	v_cvt_pk_bf16_f32 v176, v176, s0
	s_nop 0
	v_addc_co_u32_e32 v211, vcc, 0, v201, vcc
	global_store_short v[210:211], v176, off
	v_fma_f32 v176, -v107, v193, v95
	v_fma_f32 v176, v176, v163, v111
	v_add_co_u32_e32 v210, vcc, s71, v200
	v_cvt_pk_bf16_f32 v176, v176, s0
	s_nop 0
	v_addc_co_u32_e32 v211, vcc, 0, v201, vcc
	global_store_short v[210:211], v176, off
	v_fma_f32 v176, -v96, v193, v88
	v_fma_f32 v176, v176, v163, v100
	v_add_co_u32_e32 v210, vcc, s59, v200
	v_cvt_pk_bf16_f32 v176, v176, s0
	s_nop 0
	v_addc_co_u32_e32 v211, vcc, 0, v201, vcc
	global_store_short v[210:211], v176, off
	v_fma_f32 v176, -v97, v193, v89
	v_fma_f32 v176, v176, v163, v101
	v_add_co_u32_e32 v210, vcc, s60, v200
	v_cvt_pk_bf16_f32 v176, v176, s0
	s_nop 0
	v_addc_co_u32_e32 v211, vcc, 0, v201, vcc
	global_store_short v[210:211], v176, off
	v_fma_f32 v176, -v98, v193, v90
	v_fma_f32 v176, v176, v163, v102
	v_add_co_u32_e32 v210, vcc, s66, v200
	v_cvt_pk_bf16_f32 v176, v176, s0
	s_nop 0
	v_addc_co_u32_e32 v211, vcc, 0, v201, vcc
	global_store_short v[210:211], v176, off
	v_fma_f32 v176, -v99, v193, v91
	v_fma_f32 v176, v176, v163, v103
	v_add_co_u32_e32 v210, vcc, s68, v200
	v_cvt_pk_bf16_f32 v176, v176, s0
	s_nop 0
	v_addc_co_u32_e32 v211, vcc, 0, v201, vcc
	global_store_short v[210:211], v176, off
	v_fma_f32 v176, -v112, v193, v84
	v_fma_f32 v176, v176, v163, v116
	v_add_co_u32_e32 v210, vcc, s74, v200
	v_cvt_pk_bf16_f32 v176, v176, s0
	s_nop 0
	v_addc_co_u32_e32 v211, vcc, 0, v201, vcc
	global_store_short v[210:211], v176, off
	v_fma_f32 v176, -v113, v193, v85
	v_fma_f32 v176, v176, v163, v117
	v_add_co_u32_e32 v210, vcc, s75, v200
	v_cvt_pk_bf16_f32 v176, v176, s0
	s_nop 0
	v_addc_co_u32_e32 v211, vcc, 0, v201, vcc
	global_store_short v[210:211], v176, off
	v_fma_f32 v176, -v114, v193, v86
	v_fma_f32 v176, v176, v163, v118
	v_add_co_u32_e32 v210, vcc, s76, v200
	v_cvt_pk_bf16_f32 v176, v176, s0
	s_nop 0
	v_addc_co_u32_e32 v211, vcc, 0, v201, vcc
	global_store_short v[210:211], v176, off
	v_fma_f32 v176, -v115, v193, v87
	v_fma_f32 v176, v176, v163, v119
	v_add_co_u32_e32 v210, vcc, s77, v200
	v_cvt_pk_bf16_f32 v176, v176, s0
	s_nop 0
	v_addc_co_u32_e32 v211, vcc, 0, v201, vcc
	global_store_short v[210:211], v176, off
	v_fma_f32 v176, -v124, v193, v80
	v_fma_f32 v176, v176, v163, v120
	v_add_co_u32_e32 v210, vcc, s78, v200
	v_cvt_pk_bf16_f32 v176, v176, s0
	s_nop 0
	v_addc_co_u32_e32 v211, vcc, 0, v201, vcc
	global_store_short v[210:211], v176, off
	v_fma_f32 v176, -v125, v193, v81
	v_fma_f32 v176, v176, v163, v121
	v_add_co_u32_e32 v210, vcc, s79, v200
	v_cvt_pk_bf16_f32 v176, v176, s0
	s_nop 0
	v_addc_co_u32_e32 v211, vcc, 0, v201, vcc
	global_store_short v[210:211], v176, off
	v_fma_f32 v176, -v126, v193, v82
	v_fma_f32 v176, v176, v163, v122
	v_add_co_u32_e32 v210, vcc, s80, v200
	v_cvt_pk_bf16_f32 v176, v176, s0
	s_nop 0
	v_addc_co_u32_e32 v211, vcc, 0, v201, vcc
	global_store_short v[210:211], v176, off
	v_fma_f32 v176, -v127, v193, v83
	v_fma_f32 v163, v176, v163, v123
	v_add_co_u32_e32 v200, vcc, s81, v200
	v_cvt_pk_bf16_f32 v163, v163, s0
	s_nop 0
	v_addc_co_u32_e32 v201, vcc, 0, v201, vcc
	global_store_short v[200:201], v163, off
	v_lshlrev_b32_e32 v163, s45, v162
	v_and_b32_e32 v163, 0x1ffe, v163
	v_lshrrev_b32_e32 v162, s2, v162
	v_or_b32_e32 v176, v163, v162
	v_bitop3_b32 v162, v163, s72, v162 bitop3:0xc8
	v_lshlrev_b32_e32 v163, 1, v176
	v_lshrrev_b32_e32 v176, 1, v176
	v_and_b32_e32 v163, 8, v163
	v_and_b32_e32 v176, 4, v176
	s_waitcnt vmcnt(16)
	v_mul_f32_e32 v193, 0x3a800000, v208
	v_or3_b32 v162, v163, v162, v176
	v_mul_f32_e32 v163, v193, v193
	v_fma_f32 v163, v209, s40, -v163
	v_add_f32_e32 v163, 0x3727c5ac, v163
	v_mul_f32_e32 v176, 0x4f800000, v163
	v_cmp_gt_f32_e32 vcc, s73, v163
	s_nop 1
	v_cndmask_b32_e32 v163, v163, v176, vcc
	v_sqrt_f32_e32 v195, v163
	v_lshlrev_b32_e32 v176, 1, v162
	v_lshl_add_u64 v[160:161], v[160:161], 0, v[176:177]
	v_add_u32_e32 v162, 0x80, v194
	v_add_u32_e32 v176, -1, v195
	v_fma_f32 v198, -v176, v195, v163
	v_cmp_ge_f32_e64 s[0:1], 0, v198
	v_add_u32_e32 v198, 1, v195
	s_nop 0
	v_cndmask_b32_e64 v176, v195, v176, s[0:1]
	v_fma_f32 v195, -v198, v195, v163
	v_cmp_lt_f32_e64 s[0:1], 0, v195
	s_nop 1
	v_cndmask_b32_e64 v176, v176, v198, s[0:1]
	v_mul_f32_e32 v195, 0x37800000, v176
	v_cndmask_b32_e32 v176, v176, v195, vcc
	v_cmp_class_f32_e32 vcc, v163, v205
	s_nop 1
	v_cndmask_b32_e32 v176, v176, v163, vcc
	v_ashrrev_i32_e32 v163, 31, v162
	v_lshl_add_u64 v[200:201], v[162:163], 3, s[10:11]
	global_load_dwordx2 v[200:201], v[200:201], off
	v_div_scale_f32 v195, s[0:1], v176, v176, 1.0
	v_rcp_f32_e32 v198, v195
	s_nop 0
	v_fma_f32 v163, -v195, v198, 1.0
	v_fmac_f32_e32 v198, v163, v198
	v_div_scale_f32 v163, vcc, 1.0, v176, 1.0
	v_mul_f32_e32 v207, v163, v198
	v_fma_f32 v208, -v195, v207, v163
	v_fmac_f32_e32 v207, v208, v198
	v_fma_f32 v163, -v195, v207, v163
	v_div_fmas_f32 v163, v163, v198, v207
	v_div_fixup_f32 v163, v163, v176, 1.0
	v_fma_f32 v176, -v104, v193, v76
	v_fma_f32 v176, v176, v163, v108
	v_cvt_pk_bf16_f32 v176, v176, s0
	global_store_short v[160:161], v176, off
	v_fma_f32 v176, -v105, v193, v77
	v_fma_f32 v176, v176, v163, v109
	v_add_co_u32_e32 v208, vcc, s61, v160
	v_cvt_pk_bf16_f32 v176, v176, s0
	s_nop 0
	v_addc_co_u32_e32 v209, vcc, 0, v161, vcc
	global_store_short v[208:209], v176, off
	v_fma_f32 v176, -v106, v193, v78
	v_fma_f32 v176, v176, v163, v110
	v_add_co_u32_e32 v208, vcc, s67, v160
	v_cvt_pk_bf16_f32 v176, v176, s0
	s_nop 0
	v_addc_co_u32_e32 v209, vcc, 0, v161, vcc
	global_store_short v[208:209], v176, off
	v_fma_f32 v176, -v107, v193, v79
	v_fma_f32 v176, v176, v163, v111
	v_add_co_u32_e32 v208, vcc, s71, v160
	v_cvt_pk_bf16_f32 v176, v176, s0
	s_nop 0
	v_addc_co_u32_e32 v209, vcc, 0, v161, vcc
	global_store_short v[208:209], v176, off
	v_fma_f32 v176, -v96, v193, v72
	v_fma_f32 v176, v176, v163, v100
	v_add_co_u32_e32 v208, vcc, s59, v160
	v_cvt_pk_bf16_f32 v176, v176, s0
	s_nop 0
	v_addc_co_u32_e32 v209, vcc, 0, v161, vcc
	global_store_short v[208:209], v176, off
	v_fma_f32 v176, -v97, v193, v73
	v_fma_f32 v176, v176, v163, v101
	v_add_co_u32_e32 v208, vcc, s60, v160
	v_cvt_pk_bf16_f32 v176, v176, s0
	s_nop 0
	v_addc_co_u32_e32 v209, vcc, 0, v161, vcc
	global_store_short v[208:209], v176, off
	v_fma_f32 v176, -v98, v193, v74
	v_fma_f32 v176, v176, v163, v102
	v_add_co_u32_e32 v208, vcc, s66, v160
	v_cvt_pk_bf16_f32 v176, v176, s0
	s_nop 0
	v_addc_co_u32_e32 v209, vcc, 0, v161, vcc
	global_store_short v[208:209], v176, off
	v_fma_f32 v176, -v99, v193, v75
	v_fma_f32 v176, v176, v163, v103
	v_add_co_u32_e32 v208, vcc, s68, v160
	v_cvt_pk_bf16_f32 v176, v176, s0
	s_nop 0
	v_addc_co_u32_e32 v209, vcc, 0, v161, vcc
	global_store_short v[208:209], v176, off
	v_fma_f32 v176, -v112, v193, v68
	v_fma_f32 v176, v176, v163, v116
	v_add_co_u32_e32 v208, vcc, s74, v160
	v_cvt_pk_bf16_f32 v176, v176, s0
	s_nop 0
	v_addc_co_u32_e32 v209, vcc, 0, v161, vcc
	global_store_short v[208:209], v176, off
	v_fma_f32 v176, -v113, v193, v69
	v_fma_f32 v176, v176, v163, v117
	v_add_co_u32_e32 v208, vcc, s75, v160
	v_cvt_pk_bf16_f32 v176, v176, s0
	s_nop 0
	v_addc_co_u32_e32 v209, vcc, 0, v161, vcc
	global_store_short v[208:209], v176, off
	v_fma_f32 v176, -v114, v193, v70
	v_fma_f32 v176, v176, v163, v118
	v_add_co_u32_e32 v208, vcc, s76, v160
	v_cvt_pk_bf16_f32 v176, v176, s0
	s_nop 0
	v_addc_co_u32_e32 v209, vcc, 0, v161, vcc
	global_store_short v[208:209], v176, off
	v_fma_f32 v176, -v115, v193, v71
	v_fma_f32 v176, v176, v163, v119
	v_add_co_u32_e32 v208, vcc, s77, v160
	v_cvt_pk_bf16_f32 v176, v176, s0
	s_nop 0
	v_addc_co_u32_e32 v209, vcc, 0, v161, vcc
	global_store_short v[208:209], v176, off
	v_fma_f32 v176, -v124, v193, v64
	v_fma_f32 v176, v176, v163, v120
	v_add_co_u32_e32 v208, vcc, s78, v160
	v_cvt_pk_bf16_f32 v176, v176, s0
	s_nop 0
	v_addc_co_u32_e32 v209, vcc, 0, v161, vcc
	global_store_short v[208:209], v176, off
	v_fma_f32 v176, -v125, v193, v65
	v_fma_f32 v176, v176, v163, v121
	v_add_co_u32_e32 v208, vcc, s79, v160
	v_cvt_pk_bf16_f32 v176, v176, s0
	s_nop 0
	v_addc_co_u32_e32 v209, vcc, 0, v161, vcc
	global_store_short v[208:209], v176, off
	v_fma_f32 v176, -v126, v193, v66
	v_fma_f32 v176, v176, v163, v122
	v_add_co_u32_e32 v208, vcc, s80, v160
	v_cvt_pk_bf16_f32 v176, v176, s0
	s_nop 0
	v_addc_co_u32_e32 v209, vcc, 0, v161, vcc
	global_store_short v[208:209], v176, off
	v_fma_f32 v176, -v127, v193, v67
	v_fma_f32 v163, v176, v163, v123
	v_add_co_u32_e32 v160, vcc, s81, v160
	v_cvt_pk_bf16_f32 v163, v163, s0
	s_nop 0
	v_addc_co_u32_e32 v161, vcc, 0, v161, vcc
	global_store_short v[160:161], v163, off
	v_ashrrev_i32_e32 v160, 13, v162
	v_and_b32_e32 v162, 0x1fcf, v162
	v_lshlrev_b32_e32 v161, s45, v162
	v_and_b32_e32 v163, 0x1ffe, v161
	v_lshrrev_b32_e32 v176, s2, v162
	v_or_b32_e32 v193, v163, v176
	v_bitop3_b32 v163, v163, s72, v176 bitop3:0xc8
	v_lshlrev_b32_e32 v176, 1, v193
	v_lshrrev_b32_e32 v193, 1, v193
	v_and_b32_e32 v176, 8, v176
	v_and_b32_e32 v193, 4, v193
	v_or3_b32 v163, v176, v163, v193
	s_waitcnt vmcnt(16)
	v_mul_f32_e32 v193, 0x3a800000, v200
	v_mul_f32_e32 v176, v193, v193
	v_fma_f32 v176, v201, s40, -v176
	v_add_u32_e32 v208, 0x90, v194
	v_add_f32_e32 v176, 0x3727c5ac, v176
	v_ashrrev_i32_e32 v209, 31, v208
	v_mul_f32_e32 v195, 0x4f800000, v176
	v_cmp_gt_f32_e32 vcc, s73, v176
	v_lshl_add_u64 v[208:209], v[208:209], 3, s[10:11]
	global_load_dwordx2 v[208:209], v[208:209], off
	v_cndmask_b32_e32 v195, v176, v195, vcc
	v_sqrt_f32_e32 v198, v195
	v_mad_i32_i24 v160, v160, 12, s43
	v_ashrrev_i32_e32 v161, 31, v160
	v_lshlrev_b64 v[160:161], 20, v[160:161]
	v_lshl_add_u64 v[160:161], v[182:183], 0, v[160:161]
	v_lshlrev_b32_e32 v176, 1, v163
	v_add_u32_e32 v163, -1, v198
	v_lshl_add_u64 v[200:201], v[160:161], 0, v[176:177]
	v_fma_f32 v176, -v163, v198, v195
	v_cmp_ge_f32_e64 s[0:1], 0, v176
	v_add_u32_e32 v176, 1, v198
	s_nop 0
	v_cndmask_b32_e64 v163, v198, v163, s[0:1]
	v_fma_f32 v198, -v176, v198, v195
	v_cmp_lt_f32_e64 s[0:1], 0, v198
	s_nop 1
	v_cndmask_b32_e64 v163, v163, v176, s[0:1]
	v_mul_f32_e32 v176, 0x37800000, v163
	v_cndmask_b32_e32 v163, v163, v176, vcc
	v_cmp_class_f32_e32 vcc, v195, v205
	s_nop 1
	v_cndmask_b32_e32 v163, v163, v195, vcc
	v_div_scale_f32 v176, s[0:1], v163, v163, 1.0
	v_rcp_f32_e32 v195, v176
	s_nop 0
	v_fma_f32 v198, -v176, v195, 1.0
	v_fmac_f32_e32 v195, v198, v195
	v_div_scale_f32 v198, vcc, 1.0, v163, 1.0
	v_mul_f32_e32 v207, v198, v195
	v_fma_f32 v210, -v176, v207, v198
	v_fmac_f32_e32 v207, v210, v195
	v_fma_f32 v176, -v176, v207, v198
	v_div_fmas_f32 v176, v176, v195, v207
	v_div_fixup_f32 v163, v176, v163, 1.0
	v_fma_f32 v176, -v104, v193, v60
	v_fma_f32 v176, v176, v163, v108
	v_cvt_pk_bf16_f32 v176, v176, s0
	global_store_short v[200:201], v176, off
	v_fma_f32 v176, -v105, v193, v61
	v_fma_f32 v176, v176, v163, v109
	v_add_co_u32_e32 v210, vcc, s61, v200
	v_cvt_pk_bf16_f32 v176, v176, s0
	s_nop 0
	v_addc_co_u32_e32 v211, vcc, 0, v201, vcc
	global_store_short v[210:211], v176, off
	v_fma_f32 v176, -v106, v193, v62
	v_fma_f32 v176, v176, v163, v110
	v_add_co_u32_e32 v210, vcc, s67, v200
	v_cvt_pk_bf16_f32 v176, v176, s0
	s_nop 0
	v_addc_co_u32_e32 v211, vcc, 0, v201, vcc
	global_store_short v[210:211], v176, off
	v_fma_f32 v176, -v107, v193, v63
	v_fma_f32 v176, v176, v163, v111
	v_add_co_u32_e32 v210, vcc, s71, v200
	v_cvt_pk_bf16_f32 v176, v176, s0
	s_nop 0
	v_addc_co_u32_e32 v211, vcc, 0, v201, vcc
	global_store_short v[210:211], v176, off
	v_fma_f32 v176, -v96, v193, v56
	v_fma_f32 v176, v176, v163, v100
	v_add_co_u32_e32 v210, vcc, s59, v200
	v_cvt_pk_bf16_f32 v176, v176, s0
	s_nop 0
	v_addc_co_u32_e32 v211, vcc, 0, v201, vcc
	global_store_short v[210:211], v176, off
	v_fma_f32 v176, -v97, v193, v57
	v_fma_f32 v176, v176, v163, v101
	v_add_co_u32_e32 v210, vcc, s60, v200
	v_cvt_pk_bf16_f32 v176, v176, s0
	s_nop 0
	v_addc_co_u32_e32 v211, vcc, 0, v201, vcc
	global_store_short v[210:211], v176, off
	v_fma_f32 v176, -v98, v193, v58
	v_fma_f32 v176, v176, v163, v102
	v_add_co_u32_e32 v210, vcc, s66, v200
	v_cvt_pk_bf16_f32 v176, v176, s0
	s_nop 0
	v_addc_co_u32_e32 v211, vcc, 0, v201, vcc
	global_store_short v[210:211], v176, off
	v_fma_f32 v176, -v99, v193, v59
	v_fma_f32 v176, v176, v163, v103
	v_add_co_u32_e32 v210, vcc, s68, v200
	v_cvt_pk_bf16_f32 v176, v176, s0
	s_nop 0
	v_addc_co_u32_e32 v211, vcc, 0, v201, vcc
	global_store_short v[210:211], v176, off
	v_fma_f32 v176, -v112, v193, v52
	v_fma_f32 v176, v176, v163, v116
	v_add_co_u32_e32 v210, vcc, s74, v200
	v_cvt_pk_bf16_f32 v176, v176, s0
	s_nop 0
	v_addc_co_u32_e32 v211, vcc, 0, v201, vcc
	global_store_short v[210:211], v176, off
	v_fma_f32 v176, -v113, v193, v53
	v_fma_f32 v176, v176, v163, v117
	v_add_co_u32_e32 v210, vcc, s75, v200
	v_cvt_pk_bf16_f32 v176, v176, s0
	s_nop 0
	v_addc_co_u32_e32 v211, vcc, 0, v201, vcc
	global_store_short v[210:211], v176, off
	v_fma_f32 v176, -v114, v193, v54
	v_fma_f32 v176, v176, v163, v118
	v_add_co_u32_e32 v210, vcc, s76, v200
	v_cvt_pk_bf16_f32 v176, v176, s0
	s_nop 0
	v_addc_co_u32_e32 v211, vcc, 0, v201, vcc
	global_store_short v[210:211], v176, off
	v_fma_f32 v176, -v115, v193, v55
	v_fma_f32 v176, v176, v163, v119
	v_add_co_u32_e32 v210, vcc, s77, v200
	v_cvt_pk_bf16_f32 v176, v176, s0
	s_nop 0
	v_addc_co_u32_e32 v211, vcc, 0, v201, vcc
	global_store_short v[210:211], v176, off
	v_fma_f32 v176, -v124, v193, v48
	v_fma_f32 v176, v176, v163, v120
	v_add_co_u32_e32 v210, vcc, s78, v200
	v_cvt_pk_bf16_f32 v176, v176, s0
	s_nop 0
	v_addc_co_u32_e32 v211, vcc, 0, v201, vcc
	global_store_short v[210:211], v176, off
	v_fma_f32 v176, -v125, v193, v49
	v_fma_f32 v176, v176, v163, v121
	v_add_co_u32_e32 v210, vcc, s79, v200
	v_cvt_pk_bf16_f32 v176, v176, s0
	s_nop 0
	v_addc_co_u32_e32 v211, vcc, 0, v201, vcc
	global_store_short v[210:211], v176, off
	v_fma_f32 v176, -v126, v193, v50
	v_fma_f32 v176, v176, v163, v122
	v_add_co_u32_e32 v210, vcc, s80, v200
	v_cvt_pk_bf16_f32 v176, v176, s0
	s_nop 0
	v_addc_co_u32_e32 v211, vcc, 0, v201, vcc
	global_store_short v[210:211], v176, off
	v_fma_f32 v176, -v127, v193, v51
	v_fma_f32 v163, v176, v163, v123
	v_add_co_u32_e32 v200, vcc, s81, v200
	v_cvt_pk_bf16_f32 v163, v163, s0
	s_nop 0
	v_addc_co_u32_e32 v201, vcc, 0, v201, vcc
	global_store_short v[200:201], v163, off
	v_or_b32_e32 v163, 16, v162
	v_lshlrev_b32_e32 v176, s45, v163
	v_and_b32_e32 v176, 0x1ffe, v176
	v_lshrrev_b32_e32 v163, s2, v163
	v_or_b32_e32 v193, v176, v163
	v_bitop3_b32 v163, v176, s72, v163 bitop3:0xc8
	v_lshlrev_b32_e32 v176, 1, v193
	v_lshrrev_b32_e32 v193, 1, v193
	v_and_b32_e32 v176, 8, v176
	v_and_b32_e32 v193, 4, v193
	v_or3_b32 v163, v176, v163, v193
	s_waitcnt vmcnt(16)
	v_mul_f32_e32 v193, 0x3a800000, v208
	v_mul_f32_e32 v176, v193, v193
	v_fma_f32 v176, v209, s40, -v176
	v_add_u32_e32 v208, 0xa0, v194
	v_add_f32_e32 v176, 0x3727c5ac, v176
	v_ashrrev_i32_e32 v209, 31, v208
	v_mul_f32_e32 v195, 0x4f800000, v176
	v_cmp_gt_f32_e32 vcc, s73, v176
	v_lshl_add_u64 v[208:209], v[208:209], 3, s[10:11]
	global_load_dwordx2 v[208:209], v[208:209], off
	v_cndmask_b32_e32 v195, v176, v195, vcc
	v_sqrt_f32_e32 v198, v195
	v_lshlrev_b32_e32 v176, 1, v163
	v_lshl_add_u64 v[200:201], v[160:161], 0, v[176:177]
	v_add_u32_e32 v163, -1, v198
	v_fma_f32 v176, -v163, v198, v195
	v_cmp_ge_f32_e64 s[0:1], 0, v176
	v_add_u32_e32 v176, 1, v198
	s_nop 0
	v_cndmask_b32_e64 v163, v198, v163, s[0:1]
	v_fma_f32 v198, -v176, v198, v195
	v_cmp_lt_f32_e64 s[0:1], 0, v198
	s_nop 1
	v_cndmask_b32_e64 v163, v163, v176, s[0:1]
	v_mul_f32_e32 v176, 0x37800000, v163
	v_cndmask_b32_e32 v163, v163, v176, vcc
	v_cmp_class_f32_e32 vcc, v195, v205
	s_nop 1
	v_cndmask_b32_e32 v163, v163, v195, vcc
	v_div_scale_f32 v176, s[0:1], v163, v163, 1.0
	v_rcp_f32_e32 v195, v176
	s_nop 0
	v_fma_f32 v198, -v176, v195, 1.0
	v_fmac_f32_e32 v195, v198, v195
	v_div_scale_f32 v198, vcc, 1.0, v163, 1.0
	v_mul_f32_e32 v207, v198, v195
	v_fma_f32 v210, -v176, v207, v198
	v_fmac_f32_e32 v207, v210, v195
	v_fma_f32 v176, -v176, v207, v198
	v_div_fmas_f32 v176, v176, v195, v207
	v_div_fixup_f32 v163, v176, v163, 1.0
	v_fma_f32 v176, -v104, v193, v44
	v_fma_f32 v176, v176, v163, v108
	v_cvt_pk_bf16_f32 v176, v176, s0
	global_store_short v[200:201], v176, off
	v_fma_f32 v176, -v105, v193, v45
	v_fma_f32 v176, v176, v163, v109
	v_add_co_u32_e32 v210, vcc, s61, v200
	v_cvt_pk_bf16_f32 v176, v176, s0
	s_nop 0
	v_addc_co_u32_e32 v211, vcc, 0, v201, vcc
	global_store_short v[210:211], v176, off
	v_fma_f32 v176, -v106, v193, v46
	v_fma_f32 v176, v176, v163, v110
	v_add_co_u32_e32 v210, vcc, s67, v200
	v_cvt_pk_bf16_f32 v176, v176, s0
	s_nop 0
	v_addc_co_u32_e32 v211, vcc, 0, v201, vcc
	global_store_short v[210:211], v176, off
	v_fma_f32 v176, -v107, v193, v47
	v_fma_f32 v176, v176, v163, v111
	v_add_co_u32_e32 v210, vcc, s71, v200
	v_cvt_pk_bf16_f32 v176, v176, s0
	s_nop 0
	v_addc_co_u32_e32 v211, vcc, 0, v201, vcc
	global_store_short v[210:211], v176, off
	v_fma_f32 v176, -v96, v193, v40
	v_fma_f32 v176, v176, v163, v100
	v_add_co_u32_e32 v210, vcc, s59, v200
	v_cvt_pk_bf16_f32 v176, v176, s0
	s_nop 0
	v_addc_co_u32_e32 v211, vcc, 0, v201, vcc
	global_store_short v[210:211], v176, off
	v_fma_f32 v176, -v97, v193, v41
	v_fma_f32 v176, v176, v163, v101
	v_add_co_u32_e32 v210, vcc, s60, v200
	v_cvt_pk_bf16_f32 v176, v176, s0
	s_nop 0
	v_addc_co_u32_e32 v211, vcc, 0, v201, vcc
	global_store_short v[210:211], v176, off
	v_fma_f32 v176, -v98, v193, v42
	v_fma_f32 v176, v176, v163, v102
	v_add_co_u32_e32 v210, vcc, s66, v200
	v_cvt_pk_bf16_f32 v176, v176, s0
	s_nop 0
	v_addc_co_u32_e32 v211, vcc, 0, v201, vcc
	global_store_short v[210:211], v176, off
	v_fma_f32 v176, -v99, v193, v43
	v_fma_f32 v176, v176, v163, v103
	v_add_co_u32_e32 v210, vcc, s68, v200
	v_cvt_pk_bf16_f32 v176, v176, s0
	s_nop 0
	v_addc_co_u32_e32 v211, vcc, 0, v201, vcc
	global_store_short v[210:211], v176, off
	v_fma_f32 v176, -v112, v193, v36
	v_fma_f32 v176, v176, v163, v116
	v_add_co_u32_e32 v210, vcc, s74, v200
	v_cvt_pk_bf16_f32 v176, v176, s0
	s_nop 0
	v_addc_co_u32_e32 v211, vcc, 0, v201, vcc
	global_store_short v[210:211], v176, off
	v_fma_f32 v176, -v113, v193, v37
	v_fma_f32 v176, v176, v163, v117
	v_add_co_u32_e32 v210, vcc, s75, v200
	v_cvt_pk_bf16_f32 v176, v176, s0
	s_nop 0
	v_addc_co_u32_e32 v211, vcc, 0, v201, vcc
	global_store_short v[210:211], v176, off
	v_fma_f32 v176, -v114, v193, v38
	v_fma_f32 v176, v176, v163, v118
	v_add_co_u32_e32 v210, vcc, s76, v200
	v_cvt_pk_bf16_f32 v176, v176, s0
	s_nop 0
	v_addc_co_u32_e32 v211, vcc, 0, v201, vcc
	global_store_short v[210:211], v176, off
	v_fma_f32 v176, -v115, v193, v39
	v_fma_f32 v176, v176, v163, v119
	v_add_co_u32_e32 v210, vcc, s77, v200
	v_cvt_pk_bf16_f32 v176, v176, s0
	s_nop 0
	v_addc_co_u32_e32 v211, vcc, 0, v201, vcc
	global_store_short v[210:211], v176, off
	v_fma_f32 v176, -v124, v193, v32
	v_fma_f32 v176, v176, v163, v120
	v_add_co_u32_e32 v210, vcc, s78, v200
	v_cvt_pk_bf16_f32 v176, v176, s0
	s_nop 0
	v_addc_co_u32_e32 v211, vcc, 0, v201, vcc
	global_store_short v[210:211], v176, off
	v_fma_f32 v176, -v125, v193, v33
	v_fma_f32 v176, v176, v163, v121
	v_add_co_u32_e32 v210, vcc, s79, v200
	v_cvt_pk_bf16_f32 v176, v176, s0
	s_nop 0
	v_addc_co_u32_e32 v211, vcc, 0, v201, vcc
	global_store_short v[210:211], v176, off
	v_fma_f32 v176, -v126, v193, v34
	v_fma_f32 v176, v176, v163, v122
	v_add_co_u32_e32 v210, vcc, s80, v200
	v_cvt_pk_bf16_f32 v176, v176, s0
	s_nop 0
	v_addc_co_u32_e32 v211, vcc, 0, v201, vcc
	global_store_short v[210:211], v176, off
	v_fma_f32 v176, -v127, v193, v35
	v_fma_f32 v163, v176, v163, v123
	v_add_co_u32_e32 v200, vcc, s81, v200
	v_cvt_pk_bf16_f32 v163, v163, s0
	s_nop 0
	v_addc_co_u32_e32 v201, vcc, 0, v201, vcc
	global_store_short v[200:201], v163, off
	v_or_b32_e32 v163, 32, v162
	v_lshlrev_b32_e32 v176, s45, v163
	v_and_b32_e32 v176, 0x1ffe, v176
	v_lshrrev_b32_e32 v163, s2, v163
	v_or_b32_e32 v193, v176, v163
	v_bitop3_b32 v163, v176, s72, v163 bitop3:0xc8
	v_lshlrev_b32_e32 v176, 1, v193
	v_lshrrev_b32_e32 v193, 1, v193
	v_and_b32_e32 v176, 8, v176
	v_and_b32_e32 v193, 4, v193
	v_or3_b32 v163, v176, v163, v193
	s_waitcnt vmcnt(16)
	v_mul_f32_e32 v193, 0x3a800000, v208
	v_mul_f32_e32 v176, v193, v193
	v_add_u32_e32 v208, 0xb0, v194
	v_fma_f32 v176, v209, s40, -v176
	v_ashrrev_i32_e32 v209, 31, v208
	v_lshl_add_u64 v[208:209], v[208:209], 3, s[10:11]
	global_load_dwordx2 v[208:209], v[208:209], off
	v_add_f32_e32 v176, 0x3727c5ac, v176
	v_mul_f32_e32 v195, 0x4f800000, v176
	v_cmp_gt_f32_e32 vcc, s73, v176
	v_or_b32_e32 v162, 48, v162
	s_nop 0
	v_cndmask_b32_e32 v195, v176, v195, vcc
	v_sqrt_f32_e32 v198, v195
	v_lshlrev_b32_e32 v176, 1, v163
	v_lshl_add_u64 v[200:201], v[160:161], 0, v[176:177]
	v_add_u32_e32 v163, -1, v198
	v_fma_f32 v176, -v163, v198, v195
	v_cmp_ge_f32_e64 s[0:1], 0, v176
	v_add_u32_e32 v176, 1, v198
	s_nop 0
	v_cndmask_b32_e64 v163, v198, v163, s[0:1]
	v_fma_f32 v198, -v176, v198, v195
	v_cmp_lt_f32_e64 s[0:1], 0, v198
	s_nop 1
	v_cndmask_b32_e64 v163, v163, v176, s[0:1]
	v_mul_f32_e32 v176, 0x37800000, v163
	v_cndmask_b32_e32 v163, v163, v176, vcc
	v_cmp_class_f32_e32 vcc, v195, v205
	s_nop 1
	v_cndmask_b32_e32 v163, v163, v195, vcc
	v_div_scale_f32 v176, s[0:1], v163, v163, 1.0
	v_rcp_f32_e32 v195, v176
	s_nop 0
	v_fma_f32 v198, -v176, v195, 1.0
	v_fmac_f32_e32 v195, v198, v195
	v_div_scale_f32 v198, vcc, 1.0, v163, 1.0
	v_mul_f32_e32 v207, v198, v195
	v_fma_f32 v210, -v176, v207, v198
	v_fmac_f32_e32 v207, v210, v195
	v_fma_f32 v176, -v176, v207, v198
	v_div_fmas_f32 v176, v176, v195, v207
	v_div_fixup_f32 v163, v176, v163, 1.0
	v_fma_f32 v176, -v104, v193, v28
	v_fma_f32 v176, v176, v163, v108
	v_cvt_pk_bf16_f32 v176, v176, s0
	global_store_short v[200:201], v176, off
	v_fma_f32 v176, -v105, v193, v29
	v_fma_f32 v176, v176, v163, v109
	v_add_co_u32_e32 v210, vcc, s61, v200
	v_cvt_pk_bf16_f32 v176, v176, s0
	s_nop 0
	v_addc_co_u32_e32 v211, vcc, 0, v201, vcc
	global_store_short v[210:211], v176, off
	v_fma_f32 v176, -v106, v193, v30
	v_fma_f32 v176, v176, v163, v110
	v_add_co_u32_e32 v210, vcc, s67, v200
	v_cvt_pk_bf16_f32 v176, v176, s0
	s_nop 0
	v_addc_co_u32_e32 v211, vcc, 0, v201, vcc
	global_store_short v[210:211], v176, off
	v_fma_f32 v176, -v107, v193, v31
	v_fma_f32 v176, v176, v163, v111
	v_add_co_u32_e32 v210, vcc, s71, v200
	v_cvt_pk_bf16_f32 v176, v176, s0
	s_nop 0
	v_addc_co_u32_e32 v211, vcc, 0, v201, vcc
	global_store_short v[210:211], v176, off
	v_fma_f32 v176, -v96, v193, v24
	v_fma_f32 v176, v176, v163, v100
	v_add_co_u32_e32 v210, vcc, s59, v200
	v_cvt_pk_bf16_f32 v176, v176, s0
	s_nop 0
	v_addc_co_u32_e32 v211, vcc, 0, v201, vcc
	global_store_short v[210:211], v176, off
	v_fma_f32 v176, -v97, v193, v25
	v_fma_f32 v176, v176, v163, v101
	v_add_co_u32_e32 v210, vcc, s60, v200
	v_cvt_pk_bf16_f32 v176, v176, s0
	s_nop 0
	v_addc_co_u32_e32 v211, vcc, 0, v201, vcc
	global_store_short v[210:211], v176, off
	v_fma_f32 v176, -v98, v193, v26
	v_fma_f32 v176, v176, v163, v102
	v_add_co_u32_e32 v210, vcc, s66, v200
	v_cvt_pk_bf16_f32 v176, v176, s0
	s_nop 0
	v_addc_co_u32_e32 v211, vcc, 0, v201, vcc
	global_store_short v[210:211], v176, off
	v_fma_f32 v176, -v99, v193, v27
	v_fma_f32 v176, v176, v163, v103
	v_add_co_u32_e32 v210, vcc, s68, v200
	v_cvt_pk_bf16_f32 v176, v176, s0
	s_nop 0
	v_addc_co_u32_e32 v211, vcc, 0, v201, vcc
	global_store_short v[210:211], v176, off
	v_fma_f32 v176, -v112, v193, v20
	v_fma_f32 v176, v176, v163, v116
	v_add_co_u32_e32 v210, vcc, s74, v200
	v_cvt_pk_bf16_f32 v176, v176, s0
	s_nop 0
	v_addc_co_u32_e32 v211, vcc, 0, v201, vcc
	global_store_short v[210:211], v176, off
	v_fma_f32 v176, -v113, v193, v21
	v_fma_f32 v176, v176, v163, v117
	v_add_co_u32_e32 v210, vcc, s75, v200
	v_cvt_pk_bf16_f32 v176, v176, s0
	s_nop 0
	v_addc_co_u32_e32 v211, vcc, 0, v201, vcc
	global_store_short v[210:211], v176, off
	v_fma_f32 v176, -v114, v193, v22
	v_fma_f32 v176, v176, v163, v118
	v_add_co_u32_e32 v210, vcc, s76, v200
	v_cvt_pk_bf16_f32 v176, v176, s0
	s_nop 0
	v_addc_co_u32_e32 v211, vcc, 0, v201, vcc
	global_store_short v[210:211], v176, off
	v_fma_f32 v176, -v115, v193, v23
	v_fma_f32 v176, v176, v163, v119
	v_add_co_u32_e32 v210, vcc, s77, v200
	v_cvt_pk_bf16_f32 v176, v176, s0
	s_nop 0
	v_addc_co_u32_e32 v211, vcc, 0, v201, vcc
	global_store_short v[210:211], v176, off
	v_fma_f32 v176, -v124, v193, v16
	v_fma_f32 v176, v176, v163, v120
	v_add_co_u32_e32 v210, vcc, s78, v200
	v_cvt_pk_bf16_f32 v176, v176, s0
	s_nop 0
	v_addc_co_u32_e32 v211, vcc, 0, v201, vcc
	global_store_short v[210:211], v176, off
	v_fma_f32 v176, -v125, v193, v17
	v_fma_f32 v176, v176, v163, v121
	v_add_co_u32_e32 v210, vcc, s79, v200
	v_cvt_pk_bf16_f32 v176, v176, s0
	s_nop 0
	v_addc_co_u32_e32 v211, vcc, 0, v201, vcc
	global_store_short v[210:211], v176, off
	v_fma_f32 v176, -v126, v193, v18
	v_fma_f32 v176, v176, v163, v122
	v_add_co_u32_e32 v210, vcc, s80, v200
	v_cvt_pk_bf16_f32 v176, v176, s0
	s_nop 0
	v_addc_co_u32_e32 v211, vcc, 0, v201, vcc
	s_waitcnt vmcnt(14)
	v_mul_f32_e32 v195, 0x3a800000, v208
	global_store_short v[210:211], v176, off
	v_fma_f32 v176, -v127, v193, v19
	v_mul_f32_e32 v198, v195, v195
	v_fma_f32 v163, v176, v163, v123
	v_add_co_u32_e32 v200, vcc, s81, v200
	v_fma_f32 v198, v209, s40, -v198
	v_cvt_pk_bf16_f32 v163, v163, s0
	v_addc_co_u32_e32 v201, vcc, 0, v201, vcc
	v_add_f32_e32 v198, 0x3727c5ac, v198
	global_store_short v[200:201], v163, off
	v_mul_f32_e32 v200, 0x4f800000, v198
	v_cmp_gt_f32_e32 vcc, s73, v198
	v_lshlrev_b32_e32 v163, s45, v162
	v_and_b32_e32 v163, 0x1ffe, v163
	v_cndmask_b32_e32 v198, v198, v200, vcc
	v_sqrt_f32_e32 v200, v198
	v_lshrrev_b32_e32 v162, s2, v162
	v_or_b32_e32 v176, v163, v162
	v_lshlrev_b32_e32 v193, 1, v176
	v_bitop3_b32 v162, v163, s72, v162 bitop3:0xc8
	v_lshrrev_b32_e32 v163, 1, v176
	v_add_u32_e32 v176, -1, v200
	v_fma_f32 v201, -v176, v200, v198
	v_cmp_ge_f32_e64 s[0:1], 0, v201
	v_add_u32_e32 v201, 1, v200
	v_and_b32_e32 v193, 8, v193
	v_cndmask_b32_e64 v176, v200, v176, s[0:1]
	v_fma_f32 v200, -v201, v200, v198
	v_cmp_lt_f32_e64 s[0:1], 0, v200
	v_and_b32_e32 v163, 4, v163
	v_or3_b32 v162, v193, v162, v163
	v_cndmask_b32_e64 v176, v176, v201, s[0:1]
	v_mul_f32_e32 v200, 0x37800000, v176
	v_cndmask_b32_e32 v176, v176, v200, vcc
	v_cmp_class_f32_e32 vcc, v198, v205
	s_nop 1
	v_cndmask_b32_e32 v198, v176, v198, vcc
	v_div_scale_f32 v200, s[0:1], v198, v198, 1.0
	v_rcp_f32_e32 v201, v200
	v_lshlrev_b32_e32 v176, 1, v162
	v_lshl_add_u64 v[160:161], v[160:161], 0, v[176:177]
	v_fma_f32 v162, -v200, v201, 1.0
	v_fmac_f32_e32 v201, v162, v201
	v_div_scale_f32 v162, vcc, 1.0, v198, 1.0
	v_mul_f32_e32 v163, v162, v201
	v_fma_f32 v176, -v200, v163, v162
	v_fmac_f32_e32 v163, v176, v201
	v_fma_f32 v162, -v200, v163, v162
	v_div_fmas_f32 v162, v162, v201, v163
	v_div_fixup_f32 v176, v162, v198, 1.0
	v_fma_f32 v162, -v104, v195, v12
	v_fma_f32 v162, v162, v176, v108
	v_cvt_pk_bf16_f32 v162, v162, s0
	global_store_short v[160:161], v162, off
	v_fma_f32 v162, -v105, v195, v13
	v_fma_f32 v162, v162, v176, v109
	v_cvt_pk_bf16_f32 v193, v162, s0
	v_add_co_u32_e32 v162, vcc, s61, v160
	s_nop 1
	v_addc_co_u32_e32 v163, vcc, 0, v161, vcc
	global_store_short v[162:163], v193, off
	v_fma_f32 v162, -v106, v195, v14
	v_fma_f32 v162, v162, v176, v110
	v_cvt_pk_bf16_f32 v193, v162, s0
	v_add_co_u32_e32 v162, vcc, s67, v160
	s_nop 1
	v_addc_co_u32_e32 v163, vcc, 0, v161, vcc
	global_store_short v[162:163], v193, off
	v_fma_f32 v162, -v107, v195, v15
	v_fma_f32 v162, v162, v176, v111
	v_cvt_pk_bf16_f32 v193, v162, s0
	v_add_co_u32_e32 v162, vcc, s71, v160
	s_nop 1
	v_addc_co_u32_e32 v163, vcc, 0, v161, vcc
	global_store_short v[162:163], v193, off
	v_fma_f32 v162, -v96, v195, v8
	v_fma_f32 v162, v162, v176, v100
	v_cvt_pk_bf16_f32 v193, v162, s0
	v_add_co_u32_e32 v162, vcc, s59, v160
	s_nop 1
	v_addc_co_u32_e32 v163, vcc, 0, v161, vcc
	global_store_short v[162:163], v193, off
	v_fma_f32 v162, -v97, v195, v9
	v_fma_f32 v162, v162, v176, v101
	v_cvt_pk_bf16_f32 v193, v162, s0
	v_add_co_u32_e32 v162, vcc, s60, v160
	s_nop 1
	v_addc_co_u32_e32 v163, vcc, 0, v161, vcc
	global_store_short v[162:163], v193, off
	v_fma_f32 v162, -v98, v195, v10
	v_fma_f32 v162, v162, v176, v102
	v_cvt_pk_bf16_f32 v193, v162, s0
	v_add_co_u32_e32 v162, vcc, s66, v160
	s_nop 1
	v_addc_co_u32_e32 v163, vcc, 0, v161, vcc
	global_store_short v[162:163], v193, off
	v_fma_f32 v162, -v99, v195, v11
	v_fma_f32 v162, v162, v176, v103
	v_cvt_pk_bf16_f32 v193, v162, s0
	v_add_co_u32_e32 v162, vcc, s68, v160
	s_nop 1
	v_addc_co_u32_e32 v163, vcc, 0, v161, vcc
	global_store_short v[162:163], v193, off
	v_fma_f32 v162, -v112, v195, v4
	v_fma_f32 v162, v162, v176, v116
	v_cvt_pk_bf16_f32 v193, v162, s0
	v_add_co_u32_e32 v162, vcc, s74, v160
	s_nop 1
	v_addc_co_u32_e32 v163, vcc, 0, v161, vcc
	global_store_short v[162:163], v193, off
	v_fma_f32 v162, -v113, v195, v5
	v_fma_f32 v162, v162, v176, v117
	v_cvt_pk_bf16_f32 v193, v162, s0
	v_add_co_u32_e32 v162, vcc, s75, v160
	s_nop 1
	v_addc_co_u32_e32 v163, vcc, 0, v161, vcc
	global_store_short v[162:163], v193, off
	v_fma_f32 v162, -v114, v195, v6
	v_fma_f32 v162, v162, v176, v118
	v_cvt_pk_bf16_f32 v193, v162, s0
	v_add_co_u32_e32 v162, vcc, s76, v160
	s_nop 1
	v_addc_co_u32_e32 v163, vcc, 0, v161, vcc
	global_store_short v[162:163], v193, off
	v_fma_f32 v162, -v115, v195, v7
	v_fma_f32 v162, v162, v176, v119
	v_cvt_pk_bf16_f32 v193, v162, s0
	v_add_co_u32_e32 v162, vcc, s77, v160
	s_nop 1
	v_addc_co_u32_e32 v163, vcc, 0, v161, vcc
	global_store_short v[162:163], v193, off
	v_fma_f32 v162, -v124, v195, v0
	v_fma_f32 v162, v162, v176, v120
	v_cvt_pk_bf16_f32 v193, v162, s0
	v_add_co_u32_e32 v162, vcc, s78, v160
	s_nop 1
	v_addc_co_u32_e32 v163, vcc, 0, v161, vcc
	global_store_short v[162:163], v193, off
	v_fma_f32 v162, -v125, v195, v1
	v_fma_f32 v162, v162, v176, v121
	v_cvt_pk_bf16_f32 v193, v162, s0
	v_add_co_u32_e32 v162, vcc, s79, v160
	s_nop 1
	v_addc_co_u32_e32 v163, vcc, 0, v161, vcc
	global_store_short v[162:163], v193, off
	v_fma_f32 v162, -v126, v195, v2
	v_fma_f32 v162, v162, v176, v122
	v_cvt_pk_bf16_f32 v193, v162, s0
	v_add_co_u32_e32 v162, vcc, 0x98000, v160
	s_nop 1
	v_addc_co_u32_e32 v163, vcc, 0, v161, vcc
	global_store_short v[162:163], v193, off
	v_fma_f32 v162, -v127, v195, v3
	v_fma_f32 v162, v162, v176, v123
	v_add_co_u32_e32 v160, vcc, 0x9c000, v160
	v_cvt_pk_bf16_f32 v162, v162, s0
	s_nop 0
	v_addc_co_u32_e32 v161, vcc, 0, v161, vcc
	s_mov_b64 s[0:1], 0
	global_store_short v[160:161], v162, off
